# no-max attention loop: first two PV MFMAs issued ahead of the LDS-DMA blocks; diff loop: 3 exps per late PV gap
# speedup vs baseline: 1.0033x; 1.0033x over previous
.LBB0_478:
	v_exp_f32_e32 v128, v128
	ds_read_b64_tr_b16 v[92:93], v212 offset:32768
	ds_read_b64_tr_b16 v[94:95], v212 offset:33280
	v_exp_f32_e32 v132, v132
	ds_read_b64_tr_b16 v[204:205], v212 offset:36864
	ds_read_b64_tr_b16 v[206:207], v212 offset:37376
	v_add_u32_e32 v176, s31, v243
	ds_read_b128 v[80:83], v176
	ds_read_b128 v[196:199], v176 offset:512
	s_waitcnt lgkmcnt(14)
	v_mfma_f32_32x32x16_bf16 v[0:15], v[152:155], v[100:103], v[0:15]
	v_exp_f32_e32 v136, v136
	ds_read_b64_tr_b16 v[100:101], v212 offset:33792
	ds_read_b64_tr_b16 v[102:103], v212 offset:34304
	ds_read_b128 v[200:203], v176 offset:2048
	ds_read_b128 v[192:195], v176 offset:2560
	v_mfma_f32_32x32x16_bf16 v[48:63], v[152:155], v[96:99], v[48:63]
	v_exp_f32_e32 v140, v140
	ds_read_b64_tr_b16 v[96:97], v212 offset:37888
	ds_read_b64_tr_b16 v[98:99], v212 offset:38400
	ds_read_b128 v[188:191], v176 offset:4096
	ds_read_b128 v[184:187], v176 offset:4608
	s_waitcnt lgkmcnt(14)
	v_mfma_f32_32x32x16_bf16 v[0:15], v[148:151], v[108:111], v[0:15]
	v_exp_f32_e32 v112, v112
	ds_read_b64_tr_b16 v[108:109], v212 offset:34816
	ds_read_b64_tr_b16 v[110:111], v212 offset:35328
	ds_read_b128 v[180:183], v176 offset:6144
	ds_read_b128 v[176:179], v176 offset:6656
	v_mfma_f32_32x32x16_bf16 v[48:63], v[148:151], v[104:107], v[48:63]
	v_exp_f32_e32 v116, v116
	ds_read_b64_tr_b16 v[104:105], v212 offset:38912
	ds_read_b64_tr_b16 v[106:107], v212 offset:39424
	v_mfma_f32_32x32x16_bf16 v[0:15], v[144:147], v[84:87], v[0:15]
	v_exp_f32_e32 v120, v120
	ds_read_b64_tr_b16 v[84:85], v212 offset:35840
	ds_read_b64_tr_b16 v[86:87], v212 offset:36352
	v_mfma_f32_32x32x16_bf16 v[48:63], v[144:147], v[88:91], v[48:63]
	v_exp_f32_e32 v124, v124
	ds_read_b64_tr_b16 v[88:89], v212 offset:39936
	ds_read_b64_tr_b16 v[90:91], v212 offset:40448
	s_waitcnt lgkmcnt(14)
	v_mfma_f32_32x32x16_bf16 v[16:31], v[156:159], v[92:95], v[16:31]
	v_exp_f32_e32 v129, v129
	v_exp_f32_e32 v130, v130
	v_exp_f32_e32 v131, v131
	v_mfma_f32_32x32x16_bf16 v[32:47], v[156:159], v[204:207], v[32:47]
	v_exp_f32_e32 v133, v133
	v_exp_f32_e32 v134, v134
	v_exp_f32_e32 v135, v135
	v_mfma_f32_32x32x16_bf16 v[16:31], v[152:155], v[100:103], v[16:31]
	v_exp_f32_e32 v137, v137
	v_exp_f32_e32 v138, v138
	v_exp_f32_e32 v139, v139
	s_waitcnt lgkmcnt(12)
	v_mfma_f32_32x32x16_bf16 v[32:47], v[152:155], v[96:99], v[32:47]
	v_exp_f32_e32 v141, v141
	v_exp_f32_e32 v142, v142
	v_exp_f32_e32 v143, v143
	s_waitcnt lgkmcnt(8)
	v_mfma_f32_32x32x16_bf16 v[16:31], v[148:151], v[108:111], v[16:31]
	v_exp_f32_e32 v113, v113
	v_exp_f32_e32 v114, v114
	v_exp_f32_e32 v115, v115
	s_waitcnt lgkmcnt(4)
	v_mfma_f32_32x32x16_bf16 v[32:47], v[148:151], v[104:107], v[32:47]
	v_exp_f32_e32 v117, v117
	v_exp_f32_e32 v118, v118
	v_exp_f32_e32 v119, v119
	s_waitcnt lgkmcnt(2)
	v_mfma_f32_32x32x16_bf16 v[16:31], v[144:147], v[84:87], v[16:31]
	v_exp_f32_e32 v121, v121
	v_exp_f32_e32 v122, v122
	v_exp_f32_e32 v123, v123
	s_waitcnt lgkmcnt(0)
	v_mfma_f32_32x32x16_bf16 v[32:47], v[144:147], v[88:91], v[32:47]
	v_exp_f32_e32 v125, v125
	v_exp_f32_e32 v126, v126
	v_exp_f32_e32 v127, v127
	s_waitcnt vmcnt(3) lgkmcnt(0)
	s_barrier
	s_andn2_b64 vcc, exec, s[22:23]
	s_cbranch_vccnz .LBB0_480
	s_waitcnt lgkmcnt(0)
	v_add_u32_e32 v96, s18, v247
	ds_read_b128 v[84:87], v96 offset:96
	ds_read_b128 v[88:91], v96 offset:64
	ds_read_b128 v[92:95], v96 offset:32
	ds_read_b128 v[96:99], v96
	s_waitcnt lgkmcnt(3)
	v_pk_mul_f32 v[12:13], v[12:13], v[84:85]
	s_waitcnt lgkmcnt(2)
	v_pk_mul_f32 v[8:9], v[8:9], v[88:89]
	s_waitcnt lgkmcnt(1)
	v_pk_mul_f32 v[4:5], v[4:5], v[92:93]
	v_pk_mul_f32 v[14:15], v[14:15], v[86:87]
	v_pk_mul_f32 v[10:11], v[10:11], v[90:91]
	v_pk_mul_f32 v[6:7], v[6:7], v[94:95]
	s_waitcnt lgkmcnt(0)
	v_pk_mul_f32 v[2:3], v[2:3], v[98:99]
	v_pk_mul_f32 v[0:1], v[0:1], v[96:97]
	v_pk_mul_f32 v[60:61], v[60:61], v[84:85]
	v_pk_mul_f32 v[56:57], v[56:57], v[88:89]
	v_pk_mul_f32 v[52:53], v[52:53], v[92:93]
	v_pk_mul_f32 v[62:63], v[62:63], v[86:87]
	v_pk_mul_f32 v[58:59], v[58:59], v[90:91]
	v_pk_mul_f32 v[54:55], v[54:55], v[94:95]
	v_pk_mul_f32 v[50:51], v[50:51], v[98:99]
	v_pk_mul_f32 v[48:49], v[48:49], v[96:97]
	v_pk_mul_f32 v[28:29], v[28:29], v[84:85]
	v_pk_mul_f32 v[24:25], v[24:25], v[88:89]
	v_pk_mul_f32 v[20:21], v[20:21], v[92:93]
	v_pk_mul_f32 v[30:31], v[30:31], v[86:87]
	v_pk_mul_f32 v[26:27], v[26:27], v[90:91]
	v_pk_mul_f32 v[22:23], v[22:23], v[94:95]
	v_pk_mul_f32 v[18:19], v[18:19], v[98:99]
	v_pk_mul_f32 v[16:17], v[16:17], v[96:97]
	v_pk_mul_f32 v[44:45], v[44:45], v[84:85]
	v_pk_mul_f32 v[40:41], v[40:41], v[88:89]
	v_pk_mul_f32 v[36:37], v[36:37], v[92:93]
	v_pk_mul_f32 v[46:47], v[46:47], v[86:87]
	v_pk_mul_f32 v[42:43], v[42:43], v[90:91]
	v_pk_mul_f32 v[38:39], v[38:39], v[94:95]
	v_pk_mul_f32 v[34:35], v[34:35], v[98:99]
	v_pk_mul_f32 v[32:33], v[32:33], v[96:97]

.LBB0_481:
	v_exp_f32_e32 v96, v96
	ds_read_b64_tr_b16 v[124:125], v236 offset:32768
	ds_read_b64_tr_b16 v[126:127], v236 offset:33280
	v_exp_f32_e32 v100, v100
	ds_read_b64_tr_b16 v[136:137], v236 offset:36864
	ds_read_b64_tr_b16 v[138:139], v236 offset:37376
	v_add_u32_e32 v176, s34, v243
	ds_read_b128 v[204:207], v176
	ds_read_b128 v[196:199], v176 offset:512
	s_waitcnt lgkmcnt(14)
	v_mfma_f32_32x32x16_bf16 v[0:15], v[152:155], v[208:211], v[0:15]
	v_exp_f32_e32 v104, v104
	ds_read_b64_tr_b16 v[140:141], v236 offset:33792
	ds_read_b64_tr_b16 v[142:143], v236 offset:34304
	ds_read_b128 v[200:203], v176 offset:2048
	ds_read_b128 v[192:195], v176 offset:2560
	v_mfma_f32_32x32x16_bf16 v[48:63], v[152:155], v[132:135], v[48:63]
	v_exp_f32_e32 v108, v108
	ds_read_b64_tr_b16 v[132:133], v236 offset:37888
	ds_read_b64_tr_b16 v[134:135], v236 offset:38400
	ds_read_b128 v[188:191], v176 offset:4096
	ds_read_b128 v[184:187], v176 offset:4608
	s_waitcnt lgkmcnt(14)
	v_mfma_f32_32x32x16_bf16 v[0:15], v[148:151], v[128:131], v[0:15]
	v_exp_f32_e32 v80, v80
	ds_read_b64_tr_b16 v[128:129], v236 offset:34816
	ds_read_b64_tr_b16 v[130:131], v236 offset:35328
	ds_read_b128 v[180:183], v176 offset:6144
	ds_read_b128 v[176:179], v176 offset:6656
	v_mfma_f32_32x32x16_bf16 v[48:63], v[148:151], v[112:115], v[48:63]
	v_exp_f32_e32 v84, v84
	ds_read_b64_tr_b16 v[112:113], v236 offset:38912
	ds_read_b64_tr_b16 v[114:115], v236 offset:39424
	v_mfma_f32_32x32x16_bf16 v[0:15], v[144:147], v[116:119], v[0:15]
	v_exp_f32_e32 v88, v88
	ds_read_b64_tr_b16 v[116:117], v236 offset:35840
	ds_read_b64_tr_b16 v[118:119], v236 offset:36352
	v_mfma_f32_32x32x16_bf16 v[48:63], v[144:147], v[120:123], v[48:63]
	v_exp_f32_e32 v92, v92
	ds_read_b64_tr_b16 v[120:121], v236 offset:39936
	ds_read_b64_tr_b16 v[122:123], v236 offset:40448
	s_waitcnt lgkmcnt(14)
	v_mfma_f32_32x32x16_bf16 v[16:31], v[156:159], v[124:127], v[16:31]
	v_exp_f32_e32 v97, v97
	v_exp_f32_e32 v98, v98
	v_exp_f32_e32 v99, v99
	v_mfma_f32_32x32x16_bf16 v[32:47], v[156:159], v[136:139], v[32:47]
	v_exp_f32_e32 v101, v101
	v_exp_f32_e32 v102, v102
	v_exp_f32_e32 v103, v103
	v_mfma_f32_32x32x16_bf16 v[16:31], v[152:155], v[140:143], v[16:31]
	v_exp_f32_e32 v105, v105
	v_exp_f32_e32 v106, v106
	v_exp_f32_e32 v107, v107
	s_waitcnt lgkmcnt(12)
	v_mfma_f32_32x32x16_bf16 v[32:47], v[152:155], v[132:135], v[32:47]
	v_exp_f32_e32 v109, v109
	v_exp_f32_e32 v110, v110
	v_exp_f32_e32 v111, v111
	s_waitcnt lgkmcnt(8)
	v_mfma_f32_32x32x16_bf16 v[16:31], v[148:151], v[128:131], v[16:31]
	v_exp_f32_e32 v81, v81
	v_exp_f32_e32 v82, v82
	v_exp_f32_e32 v83, v83
	s_waitcnt lgkmcnt(4)
	v_mfma_f32_32x32x16_bf16 v[32:47], v[148:151], v[112:115], v[32:47]
	v_exp_f32_e32 v85, v85
	v_exp_f32_e32 v86, v86
	v_exp_f32_e32 v87, v87
	s_waitcnt lgkmcnt(2)
	v_mfma_f32_32x32x16_bf16 v[16:31], v[144:147], v[116:119], v[16:31]
	v_exp_f32_e32 v89, v89
	v_exp_f32_e32 v90, v90
	v_exp_f32_e32 v91, v91
	s_waitcnt lgkmcnt(0)
	v_mfma_f32_32x32x16_bf16 v[32:47], v[144:147], v[120:123], v[32:47]
	v_exp_f32_e32 v93, v93
	v_exp_f32_e32 v94, v94
	v_exp_f32_e32 v95, v95
	s_waitcnt vmcnt(3) lgkmcnt(0)
	s_barrier
	s_andn2_b64 vcc, exec, s[22:23]
	s_cbranch_vccnz .LBB0_483
	s_waitcnt lgkmcnt(0)
	v_add_u32_e32 v124, s18, v247
	ds_read_b128 v[112:115], v124 offset:96
	ds_read_b128 v[116:119], v124 offset:64
	ds_read_b128 v[120:123], v124 offset:32
	ds_read_b128 v[124:127], v124
	s_waitcnt lgkmcnt(3)
	v_pk_mul_f32 v[12:13], v[12:13], v[112:113]
	s_waitcnt lgkmcnt(2)
	v_pk_mul_f32 v[8:9], v[8:9], v[116:117]
	s_waitcnt lgkmcnt(1)
	v_pk_mul_f32 v[4:5], v[4:5], v[120:121]
	v_pk_mul_f32 v[14:15], v[14:15], v[114:115]
	v_pk_mul_f32 v[10:11], v[10:11], v[118:119]
	v_pk_mul_f32 v[6:7], v[6:7], v[122:123]
	s_waitcnt lgkmcnt(0)
	v_pk_mul_f32 v[2:3], v[2:3], v[126:127]
	v_pk_mul_f32 v[0:1], v[0:1], v[124:125]
	v_pk_mul_f32 v[60:61], v[60:61], v[112:113]
	v_pk_mul_f32 v[56:57], v[56:57], v[116:117]
	v_pk_mul_f32 v[52:53], v[52:53], v[120:121]
	v_pk_mul_f32 v[62:63], v[62:63], v[114:115]
	v_pk_mul_f32 v[58:59], v[58:59], v[118:119]
	v_pk_mul_f32 v[54:55], v[54:55], v[122:123]
	v_pk_mul_f32 v[50:51], v[50:51], v[126:127]
	v_pk_mul_f32 v[48:49], v[48:49], v[124:125]
	v_pk_mul_f32 v[28:29], v[28:29], v[112:113]
	v_pk_mul_f32 v[24:25], v[24:25], v[116:117]
	v_pk_mul_f32 v[20:21], v[20:21], v[120:121]
	v_pk_mul_f32 v[30:31], v[30:31], v[114:115]
	v_pk_mul_f32 v[26:27], v[26:27], v[118:119]
	v_pk_mul_f32 v[22:23], v[22:23], v[122:123]
	v_pk_mul_f32 v[18:19], v[18:19], v[126:127]
	v_pk_mul_f32 v[16:17], v[16:17], v[124:125]
	v_pk_mul_f32 v[44:45], v[44:45], v[112:113]
	v_pk_mul_f32 v[40:41], v[40:41], v[116:117]
	v_pk_mul_f32 v[36:37], v[36:37], v[120:121]
	v_pk_mul_f32 v[46:47], v[46:47], v[114:115]
	v_pk_mul_f32 v[42:43], v[42:43], v[118:119]
	v_pk_mul_f32 v[38:39], v[38:39], v[122:123]
	v_pk_mul_f32 v[34:35], v[34:35], v[126:127]
	v_pk_mul_f32 v[32:33], v[32:33], v[124:125]

.LBB0_970:
	v_add_u32_e32 v65, s31, v189
	ds_read_b64_tr_b16 v[178:179], v65 offset:24576
	ds_read_b64_tr_b16 v[180:181], v65 offset:25088
	v_add_f32_e32 v86, v66, v67
	v_add_f32_e32 v86, v68, v86
	v_add_f32_e32 v86, v69, v86
	v_add_f32_e32 v86, v70, v86
	v_add_f32_e32 v86, v71, v86
	v_cvt_pk_bf16_f32 v142, v66, v67
	v_cvt_pk_bf16_f32 v143, v68, v69
	v_mfma_f32_32x32x16_bf16 v[98:113], v[82:85], v[158:161], v[32:47]
	ds_read_b64_tr_b16 v[174:175], v65 offset:28672
	ds_read_b64_tr_b16 v[176:177], v65 offset:29184
	v_add_f32_e32 v66, v72, v86
	v_mfma_f32_32x32x16_bf16 v[82:97], v[166:169], v[158:161], v[32:47]
	v_add_f32_e32 v66, v73, v66
	v_add_f32_e32 v66, v74, v66
	v_add_f32_e32 v130, v75, v66
	v_cvt_pk_bf16_f32 v144, v70, v71
	v_cvt_pk_bf16_f32 v145, v72, v73
	ds_read_b64_tr_b16 v[66:67], v65 offset:25600
	ds_read_b64_tr_b16 v[68:69], v65 offset:26112
	v_add_f32_e32 v70, v76, v130
	v_add_f32_e32 v70, v77, v70
	v_add_f32_e32 v70, v78, v70
	v_add_f32_e32 v130, v79, v70
	v_cvt_pk_bf16_f32 v138, v74, v75
	v_cvt_pk_bf16_f32 v139, v76, v77
	v_mfma_f32_32x32x16_bf16 v[98:113], v[170:173], v[154:157], v[98:113]
	ds_read_b64_tr_b16 v[70:71], v65 offset:29696
	ds_read_b64_tr_b16 v[72:73], v65 offset:30208
	v_mfma_f32_32x32x16_bf16 v[82:97], v[162:165], v[154:157], v[82:97]
	v_add_f32_e32 v74, v80, v130
	v_add_f32_e32 v74, v81, v74
	v_add_f32_e32 v74, v48, v74
	v_add_f32_e32 v130, v49, v74
	v_cvt_pk_bf16_f32 v140, v78, v79
	v_cvt_pk_bf16_f32 v141, v80, v81
	ds_read_b64_tr_b16 v[74:75], v65 offset:26624
	ds_read_b64_tr_b16 v[76:77], v65 offset:27136
	v_add_f32_e32 v78, v50, v130
	v_add_f32_e32 v78, v51, v78
	v_add_f32_e32 v78, v52, v78
	v_add_f32_e32 v78, v53, v78
	v_cvt_pk_bf16_f32 v134, v48, v49
	v_cvt_pk_bf16_f32 v135, v50, v51
	v_mfma_f32_32x32x16_bf16 v[98:113], v[126:129], v[150:153], v[98:113]
	ds_read_b64_tr_b16 v[48:49], v65 offset:30720
	ds_read_b64_tr_b16 v[50:51], v65 offset:31232
	v_mfma_f32_32x32x16_bf16 v[82:97], v[122:125], v[150:153], v[82:97]
	v_add_f32_e32 v78, v54, v78
	v_add_f32_e32 v78, v55, v78
	v_add_f32_e32 v78, v56, v78
	v_add_f32_e32 v78, v57, v78
	v_cvt_pk_bf16_f32 v136, v52, v53
	v_cvt_pk_bf16_f32 v137, v54, v55
	ds_read_b64_tr_b16 v[52:53], v65 offset:27648
	ds_read_b64_tr_b16 v[54:55], v65 offset:28160
	v_add_f32_e32 v78, v58, v78
	v_add_f32_e32 v78, v59, v78
	v_add_f32_e32 v78, v60, v78
	v_add_f32_e32 v78, v61, v78
	v_cvt_pk_bf16_f32 v130, v56, v57
	v_cvt_pk_bf16_f32 v131, v58, v59
	v_mfma_f32_32x32x16_bf16 v[98:113], v[118:121], v[146:149], v[98:113]
	ds_read_b64_tr_b16 v[56:57], v65 offset:31744
	ds_read_b64_tr_b16 v[58:59], v65 offset:32256
	v_mfma_f32_32x32x16_bf16 v[82:97], v[114:117], v[146:149], v[82:97]
	v_add_f32_e32 v65, v62, v78
	v_add_f32_e32 v65, v63, v65
	v_cvt_pk_bf16_f32 v132, v60, v61
	v_cvt_pk_bf16_f32 v133, v62, v63
	v_add_f32_e32 v64, v64, v65
	s_waitcnt lgkmcnt(14)
	v_mfma_f32_32x32x16_bf16 v[0:15], v[142:145], v[178:181], v[0:15]
	s_add_u32 s31, s16, s22
	s_addc_u32 s33, s17, 0
	s_add_i32 m0, s29, s18
	s_add_u32 s34, s31, 0x9ac0800
	s_addc_u32 s35, s33, 0
	global_load_lds_dwordx4 v184, s[34:35]
	v_exp_f32_e32 v98, v98
	v_exp_f32_e32 v99, v99
	v_exp_f32_e32 v100, v100
	v_exp_f32_e32 v101, v101
	s_waitcnt lgkmcnt(12)
	v_mfma_f32_32x32x16_bf16 v[16:31], v[142:145], v[174:177], v[16:31]
	s_add_u32 s34, s20, s22
	s_addc_u32 s35, s21, 0
	s_add_i32 m0, s28, s15
	s_add_u32 s36, s34, 0x9a60a00
	s_addc_u32 s37, s35, 0
	global_load_lds_dwordx4 v185, s[36:37]
	v_exp_f32_e32 v102, v102
	v_exp_f32_e32 v103, v103
	v_exp_f32_e32 v104, v104
	v_exp_f32_e32 v105, v105
	v_add_u32_e32 v65, s28, v187
	ds_read_b128 v[60:63], v65
	ds_read_b128 v[118:121], v65 offset:512
	s_waitcnt lgkmcnt(12)
	v_mfma_f32_32x32x16_bf16 v[0:15], v[138:141], v[66:69], v[0:15]
	v_exp_f32_e32 v106, v106
	v_exp_f32_e32 v107, v107
	v_exp_f32_e32 v108, v108
	v_exp_f32_e32 v109, v109
	ds_read_b128 v[122:125], v65 offset:2048
	ds_read_b128 v[126:129], v65 offset:2560
	s_waitcnt lgkmcnt(12)
	v_mfma_f32_32x32x16_bf16 v[16:31], v[138:141], v[70:73], v[16:31]
	v_exp_f32_e32 v110, v110
	v_exp_f32_e32 v111, v111
	v_exp_f32_e32 v112, v112
	v_exp_f32_e32 v113, v113
	ds_read_b128 v[162:165], v65 offset:4096
	ds_read_b128 v[166:169], v65 offset:4608
	s_waitcnt lgkmcnt(12)
	v_mfma_f32_32x32x16_bf16 v[0:15], v[134:137], v[74:77], v[0:15]
	v_exp_f32_e32 v82, v82
	v_exp_f32_e32 v83, v83
	v_exp_f32_e32 v84, v84
	v_exp_f32_e32 v85, v85
	ds_read_b128 v[170:173], v65 offset:6144
	ds_read_b128 v[114:117], v65 offset:6656
	s_waitcnt lgkmcnt(12)
	v_mfma_f32_32x32x16_bf16 v[16:31], v[134:137], v[48:51], v[16:31]
	v_exp_f32_e32 v86, v86
	v_exp_f32_e32 v87, v87
	v_exp_f32_e32 v88, v88
	v_exp_f32_e32 v89, v89
	s_waitcnt lgkmcnt(10)
	v_mfma_f32_32x32x16_bf16 v[0:15], v[130:133], v[52:55], v[0:15]
	v_exp_f32_e32 v90, v90
	v_exp_f32_e32 v91, v91
	v_exp_f32_e32 v92, v92
	v_exp_f32_e32 v93, v93
	s_waitcnt lgkmcnt(8)
	v_mfma_f32_32x32x16_bf16 v[16:31], v[130:133], v[56:59], v[16:31]
	v_exp_f32_e32 v94, v94
	v_exp_f32_e32 v95, v95
	v_exp_f32_e32 v96, v96
	v_exp_f32_e32 v97, v97
	s_waitcnt vmcnt(2) lgkmcnt(0)
	s_barrier
	s_add_i32 s30, s28, 0x2000
	s_cmpk_lg_i32 s28, 0x4000
	s_cselect_b32 s30, s30, 0
	v_add_u32_e32 v65, s29, v189
	ds_read_b64_tr_b16 v[174:175], v65 offset:24576
	ds_read_b64_tr_b16 v[176:177], v65 offset:25088
	v_mfma_f32_32x32x16_bf16 v[66:81], v[60:63], v[158:161], v[32:47]
	v_add_f32_e32 v48, v98, v99
	v_add_f32_e32 v48, v100, v48
	v_add_f32_e32 v48, v101, v48
	v_add_f32_e32 v48, v102, v48
	v_add_f32_e32 v48, v103, v48
	v_cvt_pk_bf16_f32 v142, v98, v99
	v_cvt_pk_bf16_f32 v143, v100, v101
	ds_read_b64_tr_b16 v[178:179], v65 offset:28672
	ds_read_b64_tr_b16 v[180:181], v65 offset:29184
	v_add_f32_e32 v48, v104, v48
	v_add_f32_e32 v48, v105, v48
	v_add_f32_e32 v48, v106, v48
	v_add_f32_e32 v130, v107, v48
	v_mfma_f32_32x32x16_bf16 v[48:63], v[118:121], v[158:161], v[32:47]
	v_cvt_pk_bf16_f32 v144, v102, v103
	v_cvt_pk_bf16_f32 v145, v104, v105
	ds_read_b64_tr_b16 v[98:99], v65 offset:25600
	ds_read_b64_tr_b16 v[100:101], v65 offset:26112
	v_mfma_f32_32x32x16_bf16 v[66:81], v[122:125], v[154:157], v[66:81]
	v_add_f32_e32 v102, v108, v130
	v_add_f32_e32 v102, v109, v102
	v_add_f32_e32 v102, v110, v102
	v_add_f32_e32 v118, v111, v102
	v_cvt_pk_bf16_f32 v138, v106, v107
	v_cvt_pk_bf16_f32 v139, v108, v109
	ds_read_b64_tr_b16 v[102:103], v65 offset:29696
	ds_read_b64_tr_b16 v[104:105], v65 offset:30208
	v_mfma_f32_32x32x16_bf16 v[48:63], v[126:129], v[154:157], v[48:63]
	v_add_f32_e32 v106, v112, v118
	v_add_f32_e32 v106, v113, v106
	v_add_f32_e32 v106, v82, v106
	v_add_f32_e32 v118, v83, v106
	v_cvt_pk_bf16_f32 v140, v110, v111
	v_cvt_pk_bf16_f32 v141, v112, v113
	ds_read_b64_tr_b16 v[106:107], v65 offset:26624
	ds_read_b64_tr_b16 v[108:109], v65 offset:27136
	v_mfma_f32_32x32x16_bf16 v[66:81], v[162:165], v[150:153], v[66:81]
	v_add_f32_e32 v110, v84, v118
	v_add_f32_e32 v110, v85, v110
	v_add_f32_e32 v110, v86, v110
	v_add_f32_e32 v118, v87, v110
	v_cvt_pk_bf16_f32 v134, v82, v83
	v_cvt_pk_bf16_f32 v135, v84, v85
	ds_read_b64_tr_b16 v[110:111], v65 offset:30720
	ds_read_b64_tr_b16 v[112:113], v65 offset:31232
	v_mfma_f32_32x32x16_bf16 v[48:63], v[166:169], v[150:153], v[48:63]
	v_add_f32_e32 v82, v88, v118
	v_add_f32_e32 v82, v89, v82
	v_add_f32_e32 v82, v90, v82
	v_add_f32_e32 v82, v91, v82
	v_cvt_pk_bf16_f32 v136, v86, v87
	v_cvt_pk_bf16_f32 v137, v88, v89
	ds_read_b64_tr_b16 v[86:87], v65 offset:27648
	ds_read_b64_tr_b16 v[88:89], v65 offset:28160
	v_mfma_f32_32x32x16_bf16 v[66:81], v[170:173], v[146:149], v[66:81]
	v_add_f32_e32 v82, v92, v82
	v_add_f32_e32 v82, v93, v82
	v_add_f32_e32 v82, v94, v82
	v_add_f32_e32 v82, v95, v82
	v_cvt_pk_bf16_f32 v130, v90, v91
	v_cvt_pk_bf16_f32 v131, v92, v93
	ds_read_b64_tr_b16 v[90:91], v65 offset:31744
	ds_read_b64_tr_b16 v[92:93], v65 offset:32256
	v_mfma_f32_32x32x16_bf16 v[48:63], v[114:117], v[146:149], v[48:63]
	v_add_f32_e32 v65, v96, v82
	v_add_f32_e32 v65, v97, v65
	v_cvt_pk_bf16_f32 v132, v94, v95
	v_cvt_pk_bf16_f32 v133, v96, v97
	v_add_f32_e32 v64, v64, v65
	s_waitcnt lgkmcnt(14)
	v_mfma_f32_32x32x16_bf16 v[0:15], v[142:145], v[174:177], v[0:15]
	s_add_i32 m0, s28, s18
	s_add_u32 s36, s31, 0x9af0800
	s_addc_u32 s37, s33, 0
	global_load_lds_dwordx4 v184, s[36:37]
	v_exp_f32_e32 v66, v66
	v_exp_f32_e32 v67, v67
	v_exp_f32_e32 v68, v68
	v_exp_f32_e32 v69, v69
	s_waitcnt lgkmcnt(12)
	v_mfma_f32_32x32x16_bf16 v[16:31], v[142:145], v[178:181], v[16:31]
	s_add_i32 m0, s30, s15
	s_add_u32 s34, s34, 0x9a90a00
	s_addc_u32 s35, s35, 0
	global_load_lds_dwordx4 v185, s[34:35]
	v_exp_f32_e32 v70, v70
	v_exp_f32_e32 v71, v71
	v_exp_f32_e32 v72, v72
	v_exp_f32_e32 v73, v73
	v_add_u32_e32 v65, s30, v187
	ds_read_b128 v[82:85], v65
	ds_read_b128 v[166:169], v65 offset:512
	s_waitcnt lgkmcnt(12)
	v_mfma_f32_32x32x16_bf16 v[0:15], v[138:141], v[98:101], v[0:15]
	v_exp_f32_e32 v74, v74
	v_exp_f32_e32 v75, v75
	v_exp_f32_e32 v76, v76
	v_exp_f32_e32 v77, v77
	ds_read_b128 v[170:173], v65 offset:2048
	ds_read_b128 v[162:165], v65 offset:2560
	s_waitcnt lgkmcnt(12)
	v_mfma_f32_32x32x16_bf16 v[16:31], v[138:141], v[102:105], v[16:31]
	v_exp_f32_e32 v78, v78
	v_exp_f32_e32 v79, v79
	v_exp_f32_e32 v80, v80
	v_exp_f32_e32 v81, v81
	ds_read_b128 v[126:129], v65 offset:4096
	ds_read_b128 v[122:125], v65 offset:4608
	s_waitcnt lgkmcnt(12)
	v_mfma_f32_32x32x16_bf16 v[0:15], v[134:137], v[106:109], v[0:15]
	v_exp_f32_e32 v48, v48
	v_exp_f32_e32 v49, v49
	v_exp_f32_e32 v50, v50
	v_exp_f32_e32 v51, v51
	ds_read_b128 v[118:121], v65 offset:6144
	ds_read_b128 v[114:117], v65 offset:6656
	s_waitcnt lgkmcnt(12)
	v_mfma_f32_32x32x16_bf16 v[16:31], v[134:137], v[110:113], v[16:31]
	v_exp_f32_e32 v52, v52
	v_exp_f32_e32 v53, v53
	v_exp_f32_e32 v54, v54
	v_exp_f32_e32 v55, v55
	s_waitcnt lgkmcnt(10)
	v_mfma_f32_32x32x16_bf16 v[0:15], v[130:133], v[86:89], v[0:15]
	v_exp_f32_e32 v56, v56
	v_exp_f32_e32 v57, v57
	v_exp_f32_e32 v58, v58
	v_exp_f32_e32 v59, v59
	s_waitcnt lgkmcnt(8)
	v_mfma_f32_32x32x16_bf16 v[16:31], v[130:133], v[90:93], v[16:31]
	v_exp_f32_e32 v60, v60
	v_exp_f32_e32 v61, v61
	v_exp_f32_e32 v62, v62
	v_exp_f32_e32 v63, v63
	s_add_i32 s33, s30, 0x2000
	s_cmpk_lg_i32 s30, 0x4000
	s_mov_b32 s31, s28
	s_cselect_b32 s28, s33, 0
	s_add_i32 s24, s24, 2
	s_add_u32 s20, s20, 0x60000
	s_addc_u32 s21, s21, 0
	s_waitcnt vmcnt(2) lgkmcnt(0)
	s_barrier
	s_add_u32 s16, s16, 0x60000
	s_addc_u32 s17, s17, 0
	s_mov_b32 s29, s30
	s_cmp_gt_u32 s24, 56
	s_cbranch_scc0 .LBB0_970
	s_and_b32 s16, s23, 0x3fffffc0
	s_lshl_b32 s16, s16, 2
	s_add_i32 s16, s16, 0
	ds_read_b64_tr_b16 v[174:175], v189 offset:32768
	ds_read_b64_tr_b16 v[176:177], v189 offset:33280
	v_add_f32_e32 v65, v66, v67
	v_add_f32_e32 v65, v68, v65
	v_add_f32_e32 v65, v69, v65
	v_add_f32_e32 v65, v70, v65
	v_add_f32_e32 v65, v71, v65
	v_cvt_pk_bf16_f32 v142, v66, v67
	v_cvt_pk_bf16_f32 v143, v68, v69
	s_waitcnt lgkmcnt(9)
	v_mfma_f32_32x32x16_bf16 v[98:113], v[82:85], v[158:161], v[32:47]
	ds_read_b64_tr_b16 v[178:179], v189 offset:36864
	ds_read_b64_tr_b16 v[180:181], v189 offset:37376
	v_add_f32_e32 v65, v72, v65
	v_add_f32_e32 v65, v73, v65
	v_add_f32_e32 v65, v74, v65
	v_add_f32_e32 v65, v75, v65
	v_cvt_pk_bf16_f32 v144, v70, v71
	v_cvt_pk_bf16_f32 v145, v72, v73
	s_waitcnt lgkmcnt(10)
	v_mfma_f32_32x32x16_bf16 v[82:97], v[166:169], v[158:161], v[32:47]
	ds_read_b64_tr_b16 v[66:67], v189 offset:33792
	ds_read_b64_tr_b16 v[68:69], v189 offset:34304
	v_add_f32_e32 v65, v76, v65
	v_add_f32_e32 v65, v77, v65
	v_add_f32_e32 v65, v78, v65
	v_add_f32_e32 v65, v79, v65
	v_cvt_pk_bf16_f32 v138, v74, v75
	v_cvt_pk_bf16_f32 v139, v76, v77
	s_waitcnt lgkmcnt(11)
	v_mfma_f32_32x32x16_bf16 v[98:113], v[170:173], v[154:157], v[98:113]
	ds_read_b64_tr_b16 v[70:71], v189 offset:37888
	ds_read_b64_tr_b16 v[72:73], v189 offset:38400
	v_add_f32_e32 v65, v80, v65
	v_add_f32_e32 v65, v81, v65
	v_add_f32_e32 v65, v48, v65
	v_add_f32_e32 v65, v49, v65
	v_cvt_pk_bf16_f32 v140, v78, v79
	v_cvt_pk_bf16_f32 v141, v80, v81
	s_waitcnt lgkmcnt(12)
	v_mfma_f32_32x32x16_bf16 v[82:97], v[162:165], v[154:157], v[82:97]
	ds_read_b64_tr_b16 v[74:75], v189 offset:34816
	ds_read_b64_tr_b16 v[76:77], v189 offset:35328
	v_add_f32_e32 v65, v50, v65
	v_add_f32_e32 v65, v51, v65
	v_add_f32_e32 v65, v52, v65
	v_add_f32_e32 v65, v53, v65
	v_cvt_pk_bf16_f32 v134, v48, v49
	v_cvt_pk_bf16_f32 v135, v50, v51
	s_waitcnt lgkmcnt(13)
	v_mfma_f32_32x32x16_bf16 v[98:113], v[126:129], v[150:153], v[98:113]
	ds_read_b64_tr_b16 v[48:49], v189 offset:38912
	ds_read_b64_tr_b16 v[50:51], v189 offset:39424
	v_add_f32_e32 v65, v54, v65
	v_add_f32_e32 v65, v55, v65
	v_add_f32_e32 v65, v56, v65
	v_add_f32_e32 v65, v57, v65
	v_cvt_pk_bf16_f32 v136, v52, v53
	v_cvt_pk_bf16_f32 v137, v54, v55
	s_waitcnt lgkmcnt(14)
	v_mfma_f32_32x32x16_bf16 v[82:97], v[122:125], v[150:153], v[82:97]
	ds_read_b64_tr_b16 v[52:53], v189 offset:35840
	ds_read_b64_tr_b16 v[54:55], v189 offset:36352
	v_add_f32_e32 v65, v58, v65
	v_add_f32_e32 v65, v59, v65
	v_add_f32_e32 v65, v60, v65
	v_add_f32_e32 v65, v61, v65
	v_cvt_pk_bf16_f32 v130, v56, v57
	v_cvt_pk_bf16_f32 v131, v58, v59
	s_waitcnt lgkmcnt(14)
	v_mfma_f32_32x32x16_bf16 v[98:113], v[118:121], v[146:149], v[98:113]
	ds_read_b64_tr_b16 v[56:57], v189 offset:39936
	ds_read_b64_tr_b16 v[58:59], v189 offset:40448
	v_add_f32_e32 v65, v62, v65
	v_add_f32_e32 v65, v63, v65
	v_add_f32_e32 v65, 0, v65
	v_cvt_pk_bf16_f32 v132, v60, v61
	v_cvt_pk_bf16_f32 v133, v62, v63
	v_mfma_f32_32x32x16_bf16 v[82:97], v[114:117], v[146:149], v[82:97]
	s_add_u32 s20, s10, 0xba0000
	s_addc_u32 s21, s11, 0
	s_cmp_lg_u32 0, -1
	s_cselect_b32 s17, 0, 0
	s_add_i32 s17, s17, s19
	s_add_i32 s19, s17, 0x4000
	s_mov_b32 s22, m0
	s_mov_b32 m0, s19
	s_nop 0
	global_load_lds_dwordx4 v184, s[20:21]
	s_mov_b32 m0, s22
	s_add_u32 s20, s8, 0xb40000
	s_addc_u32 s21, s9, 0
	s_mov_b32 s19, m0
	s_mov_b32 m0, s15
	s_nop 0
	global_load_lds_dwordx4 v185, s[20:21]
	s_mov_b32 m0, s19
	v_add_f32_e32 v183, v64, v65
	s_waitcnt lgkmcnt(14)
	v_mfma_f32_32x32x16_bf16 v[0:15], v[142:145], v[174:177], v[0:15]
	v_exp_f32_e32 v98, v98
	v_exp_f32_e32 v99, v99
	v_exp_f32_e32 v100, v100
	v_exp_f32_e32 v101, v101
	s_waitcnt lgkmcnt(12)
	v_mfma_f32_32x32x16_bf16 v[16:31], v[142:145], v[178:181], v[16:31]
	v_exp_f32_e32 v102, v102
	v_exp_f32_e32 v103, v103
	v_exp_f32_e32 v104, v104
	v_exp_f32_e32 v105, v105
	ds_read_b128 v[60:63], v187
	ds_read_b128 v[78:81], v187 offset:512
	s_waitcnt lgkmcnt(12)
	v_mfma_f32_32x32x16_bf16 v[0:15], v[138:141], v[66:69], v[0:15]
	v_exp_f32_e32 v106, v106
	v_exp_f32_e32 v107, v107
	v_exp_f32_e32 v108, v108
	v_exp_f32_e32 v109, v109
	ds_read_b128 v[162:165], v187 offset:2048
	ds_read_b128 v[166:169], v187 offset:2560
	s_waitcnt lgkmcnt(12)
	v_mfma_f32_32x32x16_bf16 v[16:31], v[138:141], v[70:73], v[16:31]
	v_exp_f32_e32 v110, v110
	v_exp_f32_e32 v111, v111
	v_exp_f32_e32 v112, v112
	v_exp_f32_e32 v113, v113
	ds_read_b128 v[68:71], v187 offset:4096
	ds_read_b128 v[170:173], v187 offset:4608
	s_waitcnt lgkmcnt(12)
	v_mfma_f32_32x32x16_bf16 v[0:15], v[134:137], v[74:77], v[0:15]
	v_exp_f32_e32 v82, v82
	v_exp_f32_e32 v83, v83
	v_exp_f32_e32 v84, v84
	v_exp_f32_e32 v85, v85
	ds_read_b128 v[72:75], v187 offset:6144
	ds_read_b128 v[64:67], v187 offset:6656
	s_waitcnt lgkmcnt(12)
	v_mfma_f32_32x32x16_bf16 v[16:31], v[134:137], v[48:51], v[16:31]
	v_exp_f32_e32 v86, v86
	v_exp_f32_e32 v87, v87
	v_exp_f32_e32 v88, v88
	v_exp_f32_e32 v89, v89
	s_waitcnt lgkmcnt(10)
	v_mfma_f32_32x32x16_bf16 v[0:15], v[130:133], v[52:55], v[0:15]
	v_exp_f32_e32 v90, v90
	v_exp_f32_e32 v91, v91
	v_exp_f32_e32 v92, v92
	v_exp_f32_e32 v93, v93
	s_waitcnt lgkmcnt(8)
	v_mfma_f32_32x32x16_bf16 v[16:31], v[130:133], v[56:59], v[16:31]
	v_exp_f32_e32 v94, v94
	v_exp_f32_e32 v95, v95
	v_exp_f32_e32 v96, v96
	v_exp_f32_e32 v97, v97
	s_waitcnt vmcnt(2) lgkmcnt(0)
	s_barrier
	ds_read_b64_tr_b16 v[174:175], v189 offset:40960
	ds_read_b64_tr_b16 v[176:177], v189 offset:41472
	v_add_f32_e32 v48, v98, v99
	v_add_f32_e32 v48, v100, v48
	v_add_f32_e32 v48, v101, v48
	v_add_f32_e32 v48, v102, v48
	v_add_f32_e32 v48, v103, v48
	v_cvt_pk_bf16_f32 v142, v98, v99
	v_cvt_pk_bf16_f32 v143, v100, v101
	s_waitcnt lgkmcnt(9)
	v_mfma_f32_32x32x16_bf16 v[114:129], v[60:63], v[158:161], v[32:47]
	ds_read_b64_tr_b16 v[98:99], v189 offset:45056
	ds_read_b64_tr_b16 v[100:101], v189 offset:45568
	v_add_f32_e32 v48, v104, v48
	v_add_f32_e32 v48, v105, v48
	v_add_f32_e32 v48, v106, v48
	v_add_f32_e32 v130, v107, v48
	s_waitcnt lgkmcnt(10)
	v_mfma_f32_32x32x16_bf16 v[48:63], v[78:81], v[158:161], v[32:47]
	v_cvt_pk_bf16_f32 v144, v102, v103
	v_cvt_pk_bf16_f32 v145, v104, v105
	ds_read_b64_tr_b16 v[76:77], v189 offset:41984
	ds_read_b64_tr_b16 v[78:79], v189 offset:42496
	v_add_f32_e32 v80, v108, v130
	v_add_f32_e32 v80, v109, v80
	v_add_f32_e32 v80, v110, v80
	v_add_f32_e32 v80, v111, v80
	v_cvt_pk_bf16_f32 v138, v106, v107
	v_cvt_pk_bf16_f32 v139, v108, v109
	s_waitcnt lgkmcnt(11)
	v_mfma_f32_32x32x16_bf16 v[114:129], v[162:165], v[154:157], v[114:129]
	ds_read_b64_tr_b16 v[102:103], v189 offset:46080
	ds_read_b64_tr_b16 v[104:105], v189 offset:46592
	s_waitcnt lgkmcnt(12)
	v_mfma_f32_32x32x16_bf16 v[48:63], v[166:169], v[154:157], v[48:63]
	v_add_f32_e32 v80, v112, v80
	v_add_f32_e32 v80, v113, v80
	v_add_f32_e32 v80, v82, v80
	v_add_f32_e32 v80, v83, v80
	v_cvt_pk_bf16_f32 v140, v110, v111
	v_cvt_pk_bf16_f32 v141, v112, v113
	ds_read_b64_tr_b16 v[106:107], v189 offset:43008
	ds_read_b64_tr_b16 v[108:109], v189 offset:43520
	s_waitcnt lgkmcnt(13)
	v_mfma_f32_32x32x16_bf16 v[114:129], v[68:71], v[150:153], v[114:129]
	v_add_f32_e32 v68, v84, v80
	v_add_f32_e32 v68, v85, v68
	v_add_f32_e32 v68, v86, v68
	v_add_f32_e32 v80, v87, v68
	v_cvt_pk_bf16_f32 v134, v82, v83
	v_cvt_pk_bf16_f32 v135, v84, v85
	ds_read_b64_tr_b16 v[68:69], v189 offset:47104
	ds_read_b64_tr_b16 v[70:71], v189 offset:47616
	s_waitcnt lgkmcnt(14)
	v_mfma_f32_32x32x16_bf16 v[48:63], v[170:173], v[150:153], v[48:63]
	v_add_f32_e32 v80, v88, v80
	v_add_f32_e32 v80, v89, v80
	v_add_f32_e32 v80, v90, v80
	v_add_f32_e32 v80, v91, v80
	v_cvt_pk_bf16_f32 v136, v86, v87
	v_cvt_pk_bf16_f32 v137, v88, v89
	ds_read_b64_tr_b16 v[84:85], v189 offset:44032
	ds_read_b64_tr_b16 v[86:87], v189 offset:44544
	s_waitcnt lgkmcnt(14)
	v_mfma_f32_32x32x16_bf16 v[114:129], v[72:75], v[146:149], v[114:129]
	v_add_f32_e32 v72, v92, v80
	v_add_f32_e32 v72, v93, v72
	v_add_f32_e32 v72, v94, v72
	v_add_f32_e32 v80, v95, v72
	v_cvt_pk_bf16_f32 v130, v90, v91
	v_cvt_pk_bf16_f32 v131, v92, v93
	ds_read_b64_tr_b16 v[72:73], v189 offset:48128
	ds_read_b64_tr_b16 v[74:75], v189 offset:48640
	v_mfma_f32_32x32x16_bf16 v[48:63], v[64:67], v[146:149], v[48:63]
	v_add_f32_e32 v64, v96, v80
	v_add_f32_e32 v64, v97, v64
	v_add_f32_e32 v64, 0, v64
	v_cvt_pk_bf16_f32 v132, v94, v95
	v_cvt_pk_bf16_f32 v133, v96, v97
	s_add_u32 s10, s10, 0xbd0000
	s_addc_u32 s11, s11, 0
	s_mov_b32 s19, m0
	s_mov_b32 m0, s18
	s_nop 0
	global_load_lds_dwordx4 v184, s[10:11]
	s_mov_b32 m0, s19
	s_add_u32 s10, s8, 0xb70000
	s_addc_u32 s11, s9, 0
	s_add_i32 s18, s17, 0x8000
	s_mov_b32 s19, m0
	s_mov_b32 m0, s18
	s_nop 0
	global_load_lds_dwordx4 v185, s[10:11]
	s_mov_b32 m0, s19
	v_add_f32_e32 v178, v183, v64
	s_waitcnt lgkmcnt(14)
	v_mfma_f32_32x32x16_bf16 v[0:15], v[142:145], v[174:177], v[0:15]
	v_exp_f32_e32 v114, v114
	v_exp_f32_e32 v115, v115
	v_exp_f32_e32 v116, v116
	v_exp_f32_e32 v117, v117
	s_waitcnt lgkmcnt(12)
	v_mfma_f32_32x32x16_bf16 v[16:31], v[142:145], v[98:101], v[16:31]
	v_exp_f32_e32 v118, v118
	v_exp_f32_e32 v119, v119
	v_exp_f32_e32 v120, v120
	v_exp_f32_e32 v121, v121
	ds_read_b128 v[64:67], v187 offset:8192
	ds_read_b128 v[88:91], v187 offset:8704
	s_waitcnt lgkmcnt(12)
	v_mfma_f32_32x32x16_bf16 v[0:15], v[138:141], v[76:79], v[0:15]
	v_exp_f32_e32 v122, v122
	v_exp_f32_e32 v123, v123
	v_exp_f32_e32 v124, v124
	v_exp_f32_e32 v125, v125
	ds_read_b128 v[92:95], v187 offset:10240
	ds_read_b128 v[162:165], v187 offset:10752
	s_waitcnt lgkmcnt(12)
	v_mfma_f32_32x32x16_bf16 v[16:31], v[138:141], v[102:105], v[16:31]
	v_exp_f32_e32 v126, v126
	v_exp_f32_e32 v127, v127
	v_exp_f32_e32 v128, v128
	v_exp_f32_e32 v129, v129
	ds_read_b128 v[166:169], v187 offset:12288
	ds_read_b128 v[170:173], v187 offset:12800
	s_waitcnt lgkmcnt(12)
	v_mfma_f32_32x32x16_bf16 v[0:15], v[134:137], v[106:109], v[0:15]
	v_exp_f32_e32 v48, v48
	v_exp_f32_e32 v49, v49
	v_exp_f32_e32 v50, v50
	v_exp_f32_e32 v51, v51
	ds_read_b128 v[174:177], v187 offset:14336
	ds_read_b128 v[80:83], v187 offset:14848
	s_waitcnt lgkmcnt(12)
	v_mfma_f32_32x32x16_bf16 v[16:31], v[134:137], v[68:71], v[16:31]
	v_exp_f32_e32 v52, v52
	v_exp_f32_e32 v53, v53
	v_exp_f32_e32 v54, v54
	v_exp_f32_e32 v55, v55
	s_waitcnt lgkmcnt(10)
	v_mfma_f32_32x32x16_bf16 v[0:15], v[130:133], v[84:87], v[0:15]
	v_exp_f32_e32 v56, v56
	v_exp_f32_e32 v57, v57
	v_exp_f32_e32 v58, v58
	v_exp_f32_e32 v59, v59
	s_waitcnt lgkmcnt(8)
	v_mfma_f32_32x32x16_bf16 v[16:31], v[130:133], v[72:75], v[16:31]
	v_exp_f32_e32 v60, v60
	v_exp_f32_e32 v61, v61
	v_exp_f32_e32 v62, v62
	v_exp_f32_e32 v63, v63
	s_waitcnt vmcnt(2) lgkmcnt(0)
	s_barrier
	ds_read_b64_tr_b16 v[84:85], v189 offset:24576
	ds_read_b64_tr_b16 v[86:87], v189 offset:25088
	v_add_f32_e32 v68, v114, v115
	v_add_f32_e32 v68, v116, v68
	v_add_f32_e32 v68, v117, v68
	v_add_f32_e32 v68, v118, v68
	v_add_f32_e32 v68, v119, v68
	v_cvt_pk_bf16_f32 v142, v114, v115
	v_cvt_pk_bf16_f32 v143, v116, v117
	s_waitcnt lgkmcnt(9)
	v_mfma_f32_32x32x16_bf16 v[96:111], v[64:67], v[158:161], v[32:47]
	ds_read_b64_tr_b16 v[112:113], v189 offset:28672
	ds_read_b64_tr_b16 v[114:115], v189 offset:29184
	v_add_f32_e32 v64, v120, v68
	v_add_f32_e32 v64, v121, v64
	v_add_f32_e32 v64, v122, v64
	v_add_f32_e32 v116, v123, v64
	v_cvt_pk_bf16_f32 v144, v118, v119
	v_cvt_pk_bf16_f32 v145, v120, v121
	s_waitcnt lgkmcnt(10)
	v_mfma_f32_32x32x16_bf16 v[64:79], v[88:91], v[158:161], v[32:47]
	ds_read_b64_tr_b16 v[88:89], v189 offset:25600
	ds_read_b64_tr_b16 v[90:91], v189 offset:26112
	s_waitcnt lgkmcnt(11)
	v_mfma_f32_32x32x16_bf16 v[96:111], v[92:95], v[154:157], v[96:111]
	v_add_f32_e32 v92, v124, v116
	v_add_f32_e32 v92, v125, v92
	v_add_f32_e32 v92, v126, v92
	v_add_f32_e32 v116, v127, v92
	v_cvt_pk_bf16_f32 v138, v122, v123
	v_cvt_pk_bf16_f32 v139, v124, v125
	ds_read_b64_tr_b16 v[92:93], v189 offset:29696
	ds_read_b64_tr_b16 v[94:95], v189 offset:30208
	v_add_f32_e32 v116, v128, v116
	v_add_f32_e32 v116, v129, v116
	v_add_f32_e32 v116, v48, v116
	v_add_f32_e32 v120, v49, v116
	v_cvt_pk_bf16_f32 v140, v126, v127
	v_cvt_pk_bf16_f32 v141, v128, v129
	s_waitcnt lgkmcnt(12)
	v_mfma_f32_32x32x16_bf16 v[64:79], v[162:165], v[154:157], v[64:79]
	ds_read_b64_tr_b16 v[116:117], v189 offset:26624
	ds_read_b64_tr_b16 v[118:119], v189 offset:27136
	v_add_f32_e32 v120, v50, v120
	v_add_f32_e32 v120, v51, v120
	v_add_f32_e32 v120, v52, v120
	v_add_f32_e32 v120, v53, v120
	v_cvt_pk_bf16_f32 v134, v48, v49
	v_cvt_pk_bf16_f32 v135, v50, v51
	s_waitcnt lgkmcnt(13)
	v_mfma_f32_32x32x16_bf16 v[96:111], v[166:169], v[150:153], v[96:111]
	ds_read_b64_tr_b16 v[48:49], v189 offset:30720
	ds_read_b64_tr_b16 v[50:51], v189 offset:31232
	v_add_f32_e32 v120, v54, v120
	v_add_f32_e32 v120, v55, v120
	v_add_f32_e32 v120, v56, v120
	v_add_f32_e32 v120, v57, v120
	v_cvt_pk_bf16_f32 v136, v52, v53
	v_cvt_pk_bf16_f32 v137, v54, v55
	s_waitcnt lgkmcnt(14)
	v_mfma_f32_32x32x16_bf16 v[64:79], v[170:173], v[150:153], v[64:79]
	ds_read_b64_tr_b16 v[52:53], v189 offset:27648
	ds_read_b64_tr_b16 v[54:55], v189 offset:28160
	v_add_f32_e32 v120, v58, v120
	v_add_f32_e32 v120, v59, v120
	v_add_f32_e32 v120, v60, v120
	v_add_f32_e32 v120, v61, v120
	v_cvt_pk_bf16_f32 v130, v56, v57
	v_cvt_pk_bf16_f32 v131, v58, v59
	s_waitcnt lgkmcnt(14)
	v_mfma_f32_32x32x16_bf16 v[96:111], v[174:177], v[146:149], v[96:111]
	ds_read_b64_tr_b16 v[56:57], v189 offset:31744
	ds_read_b64_tr_b16 v[58:59], v189 offset:32256
	v_mfma_f32_32x32x16_bf16 v[64:79], v[80:83], v[146:149], v[64:79]
	v_add_f32_e32 v80, v62, v120
	v_add_f32_e32 v80, v63, v80
	v_add_f32_e32 v80, 0, v80
	v_cvt_pk_bf16_f32 v132, v60, v61
	v_cvt_pk_bf16_f32 v133, v62, v63
	s_add_u32 s10, s8, 0xba0000
	s_addc_u32 s11, s9, 0
	s_add_i32 s17, s17, 0xa000
	s_mov_b32 s18, m0
	s_mov_b32 m0, s17
	s_nop 0
	global_load_lds_dwordx4 v185, s[10:11]
	s_mov_b32 m0, s18
	v_add_f32_e32 v128, v178, v80
	s_waitcnt lgkmcnt(14)
	v_mfma_f32_32x32x16_bf16 v[0:15], v[142:145], v[84:87], v[0:15]
	v_exp_f32_e32 v96, v96
	v_exp_f32_e32 v97, v97
	v_exp_f32_e32 v98, v98
	v_exp_f32_e32 v99, v99
	s_waitcnt lgkmcnt(12)
	v_mfma_f32_32x32x16_bf16 v[16:31], v[142:145], v[112:115], v[16:31]
	v_exp_f32_e32 v100, v100
	v_exp_f32_e32 v101, v101
	v_exp_f32_e32 v102, v102
	v_exp_f32_e32 v103, v103
	ds_read_b128 v[60:63], v187 offset:16384
	ds_read_b128 v[120:123], v187 offset:16896
	s_waitcnt lgkmcnt(12)
	v_mfma_f32_32x32x16_bf16 v[0:15], v[138:141], v[88:91], v[0:15]
	v_exp_f32_e32 v104, v104
	v_exp_f32_e32 v105, v105
	v_exp_f32_e32 v106, v106
	v_exp_f32_e32 v107, v107
	ds_read_b128 v[124:127], v187 offset:18432
	ds_read_b128 v[162:165], v187 offset:18944
	s_waitcnt lgkmcnt(12)
	v_mfma_f32_32x32x16_bf16 v[16:31], v[138:141], v[92:95], v[16:31]
	v_exp_f32_e32 v108, v108
	v_exp_f32_e32 v109, v109
	v_exp_f32_e32 v110, v110
	v_exp_f32_e32 v111, v111
	ds_read_b128 v[166:169], v187 offset:20480
	ds_read_b128 v[170:173], v187 offset:20992
	s_waitcnt lgkmcnt(12)
	v_mfma_f32_32x32x16_bf16 v[0:15], v[134:137], v[116:119], v[0:15]
	v_exp_f32_e32 v64, v64
	v_exp_f32_e32 v65, v65
	v_exp_f32_e32 v66, v66
	v_exp_f32_e32 v67, v67
	ds_read_b128 v[116:119], v187 offset:22528
	ds_read_b128 v[112:115], v187 offset:23040
	s_waitcnt lgkmcnt(12)
	v_mfma_f32_32x32x16_bf16 v[16:31], v[134:137], v[48:51], v[16:31]
	v_exp_f32_e32 v68, v68
	v_exp_f32_e32 v69, v69
	v_exp_f32_e32 v70, v70
	v_exp_f32_e32 v71, v71
	s_waitcnt lgkmcnt(10)
	v_mfma_f32_32x32x16_bf16 v[0:15], v[130:133], v[52:55], v[0:15]
	v_exp_f32_e32 v72, v72
	v_exp_f32_e32 v73, v73
	v_exp_f32_e32 v74, v74
	v_exp_f32_e32 v75, v75
	s_waitcnt lgkmcnt(8)
	v_mfma_f32_32x32x16_bf16 v[16:31], v[130:133], v[56:59], v[16:31]
	v_exp_f32_e32 v76, v76
	v_exp_f32_e32 v77, v77
	v_exp_f32_e32 v78, v78
	v_exp_f32_e32 v79, v79
	s_waitcnt vmcnt(1) lgkmcnt(0)
	s_barrier
	ds_read_b64_tr_b16 v[174:175], v189 offset:32768
	ds_read_b64_tr_b16 v[176:177], v189 offset:33280
	v_add_f32_e32 v48, v96, v97
	v_add_f32_e32 v48, v98, v48
	v_add_f32_e32 v48, v99, v48
	v_add_f32_e32 v48, v100, v48
	v_add_f32_e32 v48, v101, v48
	v_cvt_pk_bf16_f32 v142, v96, v97
	v_cvt_pk_bf16_f32 v143, v98, v99
	s_waitcnt lgkmcnt(9)
	v_mfma_f32_32x32x16_bf16 v[80:95], v[60:63], v[158:161], v[32:47]
	ds_read_b64_tr_b16 v[96:97], v189 offset:36864
	ds_read_b64_tr_b16 v[98:99], v189 offset:37376
	v_add_f32_e32 v48, v102, v48
	v_add_f32_e32 v48, v103, v48
	v_add_f32_e32 v48, v104, v48
	v_add_f32_e32 v129, v105, v48
	s_waitcnt lgkmcnt(10)
	v_mfma_f32_32x32x16_bf16 v[48:63], v[120:123], v[158:161], v[32:47]
	v_cvt_pk_bf16_f32 v144, v100, v101
	v_cvt_pk_bf16_f32 v145, v102, v103
	ds_read_b64_tr_b16 v[100:101], v189 offset:33792
	ds_read_b64_tr_b16 v[102:103], v189 offset:34304
	v_add_f32_e32 v120, v106, v129
	v_add_f32_e32 v120, v107, v120
	v_add_f32_e32 v120, v108, v120
	v_add_f32_e32 v120, v109, v120
	v_cvt_pk_bf16_f32 v138, v104, v105
	v_cvt_pk_bf16_f32 v139, v106, v107
	s_waitcnt lgkmcnt(11)
	v_mfma_f32_32x32x16_bf16 v[80:95], v[124:127], v[154:157], v[80:95]
	ds_read_b64_tr_b16 v[104:105], v189 offset:37888
	ds_read_b64_tr_b16 v[106:107], v189 offset:38400
	s_waitcnt lgkmcnt(12)
	v_mfma_f32_32x32x16_bf16 v[48:63], v[162:165], v[154:157], v[48:63]
	v_add_f32_e32 v120, v110, v120
	v_add_f32_e32 v120, v111, v120
	v_add_f32_e32 v120, v64, v120
	v_add_f32_e32 v124, v65, v120
	v_cvt_pk_bf16_f32 v140, v108, v109
	v_cvt_pk_bf16_f32 v141, v110, v111
	ds_read_b64_tr_b16 v[120:121], v189 offset:34816
	ds_read_b64_tr_b16 v[122:123], v189 offset:35328
	v_add_f32_e32 v108, v66, v124
	v_add_f32_e32 v108, v67, v108
	v_add_f32_e32 v108, v68, v108
	v_add_f32_e32 v108, v69, v108
	v_cvt_pk_bf16_f32 v134, v64, v65
	v_cvt_pk_bf16_f32 v135, v66, v67
	s_waitcnt lgkmcnt(13)
	v_mfma_f32_32x32x16_bf16 v[80:95], v[166:169], v[150:153], v[80:95]
	ds_read_b64_tr_b16 v[64:65], v189 offset:38912
	ds_read_b64_tr_b16 v[66:67], v189 offset:39424
	s_waitcnt lgkmcnt(14)
	v_mfma_f32_32x32x16_bf16 v[48:63], v[170:173], v[150:153], v[48:63]
	v_add_f32_e32 v108, v70, v108
	v_add_f32_e32 v108, v71, v108
	v_add_f32_e32 v108, v72, v108
	v_add_f32_e32 v108, v73, v108
	v_cvt_pk_bf16_f32 v136, v68, v69
	v_cvt_pk_bf16_f32 v137, v70, v71
	ds_read_b64_tr_b16 v[68:69], v189 offset:35840
	ds_read_b64_tr_b16 v[70:71], v189 offset:36352
	v_add_f32_e32 v108, v74, v108
	v_add_f32_e32 v108, v75, v108
	v_add_f32_e32 v108, v76, v108
	v_add_f32_e32 v108, v77, v108
	v_cvt_pk_bf16_f32 v130, v72, v73
	v_cvt_pk_bf16_f32 v131, v74, v75
	s_waitcnt lgkmcnt(14)
	v_mfma_f32_32x32x16_bf16 v[80:95], v[116:119], v[146:149], v[80:95]
	ds_read_b64_tr_b16 v[72:73], v189 offset:39936
	ds_read_b64_tr_b16 v[74:75], v189 offset:40448
	v_mfma_f32_32x32x16_bf16 v[48:63], v[112:115], v[146:149], v[48:63]
	v_add_f32_e32 v108, v78, v108
	v_add_f32_e32 v108, v79, v108
	v_add_f32_e32 v108, 0, v108
	v_cvt_pk_bf16_f32 v132, v76, v77
	v_cvt_pk_bf16_f32 v133, v78, v79
	s_add_u32 s8, s8, 0xbd0000
	s_addc_u32 s9, s9, 0
	s_mov_b32 s10, m0
	s_mov_b32 m0, s15
	s_nop 0
	global_load_lds_dwordx4 v185, s[8:9]
	s_mov_b32 m0, s10
	v_add_f32_e32 v108, v128, v108
	s_waitcnt lgkmcnt(14)
	v_mfma_f32_32x32x16_bf16 v[0:15], v[142:145], v[174:177], v[0:15]
	v_exp_f32_e32 v80, v80
	v_exp_f32_e32 v81, v81
	v_exp_f32_e32 v82, v82
	v_exp_f32_e32 v83, v83
	s_waitcnt lgkmcnt(12)
	v_mfma_f32_32x32x16_bf16 v[16:31], v[142:145], v[96:99], v[16:31]
	v_exp_f32_e32 v84, v84
	v_exp_f32_e32 v85, v85
	v_exp_f32_e32 v86, v86
	v_exp_f32_e32 v87, v87
	ds_read_b128 v[110:113], v187
	ds_read_b128 v[114:117], v187 offset:512
	s_waitcnt lgkmcnt(12)
	v_mfma_f32_32x32x16_bf16 v[0:15], v[138:141], v[100:103], v[0:15]
	v_exp_f32_e32 v88, v88
	v_exp_f32_e32 v89, v89
	v_exp_f32_e32 v90, v90
	v_exp_f32_e32 v91, v91
	ds_read_b128 v[124:127], v187 offset:2048
	ds_read_b128 v[162:165], v187 offset:2560
	s_waitcnt lgkmcnt(12)
	v_mfma_f32_32x32x16_bf16 v[16:31], v[138:141], v[104:107], v[16:31]
	v_exp_f32_e32 v92, v92
	v_exp_f32_e32 v93, v93
	v_exp_f32_e32 v94, v94
	v_exp_f32_e32 v95, v95
	ds_read_b128 v[166:169], v187 offset:4096
	ds_read_b128 v[170:173], v187 offset:4608
	s_waitcnt lgkmcnt(12)
	v_mfma_f32_32x32x16_bf16 v[0:15], v[134:137], v[120:123], v[0:15]
	v_exp_f32_e32 v48, v48
	v_exp_f32_e32 v49, v49
	v_exp_f32_e32 v50, v50
	v_exp_f32_e32 v51, v51
	ds_read_b128 v[118:121], v187 offset:6144
	ds_read_b128 v[104:107], v187 offset:6656
	s_waitcnt lgkmcnt(12)
	v_mfma_f32_32x32x16_bf16 v[16:31], v[134:137], v[64:67], v[16:31]
	v_exp_f32_e32 v52, v52
	v_exp_f32_e32 v53, v53
	v_exp_f32_e32 v54, v54
	v_exp_f32_e32 v55, v55
	s_waitcnt lgkmcnt(10)
	v_mfma_f32_32x32x16_bf16 v[0:15], v[130:133], v[68:71], v[0:15]
	v_exp_f32_e32 v56, v56
	v_exp_f32_e32 v57, v57
	v_exp_f32_e32 v58, v58
	v_exp_f32_e32 v59, v59
	s_waitcnt lgkmcnt(8)
	v_mfma_f32_32x32x16_bf16 v[16:31], v[130:133], v[72:75], v[16:31]
	v_exp_f32_e32 v60, v60
	v_exp_f32_e32 v61, v61
	v_exp_f32_e32 v62, v62
	v_exp_f32_e32 v63, v63
	s_waitcnt vmcnt(0) lgkmcnt(0)
	s_barrier
	ds_read_b64_tr_b16 v[96:97], v189 offset:40960
	ds_read_b64_tr_b16 v[98:99], v189 offset:41472
	v_add_f32_e32 v64, v80, v81
	v_add_f32_e32 v64, v82, v64
	v_add_f32_e32 v64, v83, v64
	v_add_f32_e32 v64, v84, v64
	v_add_f32_e32 v100, v85, v64
	v_cvt_pk_bf16_f32 v142, v80, v81
	v_cvt_pk_bf16_f32 v143, v82, v83
	s_waitcnt lgkmcnt(9)
	v_mfma_f32_32x32x16_bf16 v[64:79], v[110:113], v[158:161], v[32:47]
	ds_read_b64_tr_b16 v[80:81], v189 offset:45056
	ds_read_b64_tr_b16 v[82:83], v189 offset:45568
	s_waitcnt lgkmcnt(10)
	v_mfma_f32_32x32x16_bf16 v[32:47], v[114:117], v[158:161], v[32:47]
	v_add_f32_e32 v100, v86, v100
	v_add_f32_e32 v100, v87, v100
	v_add_f32_e32 v100, v88, v100
	v_add_f32_e32 v109, v89, v100
	v_cvt_pk_bf16_f32 v144, v84, v85
	v_cvt_pk_bf16_f32 v145, v86, v87
	ds_read_b64_tr_b16 v[100:101], v189 offset:41984
	ds_read_b64_tr_b16 v[102:103], v189 offset:42496
	v_add_f32_e32 v84, v90, v109
	v_add_f32_e32 v84, v91, v84
	v_add_f32_e32 v84, v92, v84
	v_add_f32_e32 v109, v93, v84
	v_cvt_pk_bf16_f32 v138, v88, v89
	v_cvt_pk_bf16_f32 v139, v90, v91
	s_waitcnt lgkmcnt(11)
	v_mfma_f32_32x32x16_bf16 v[64:79], v[124:127], v[154:157], v[64:79]
	ds_read_b64_tr_b16 v[84:85], v189 offset:46080
	ds_read_b64_tr_b16 v[86:87], v189 offset:46592
	s_waitcnt lgkmcnt(12)
	v_mfma_f32_32x32x16_bf16 v[32:47], v[162:165], v[154:157], v[32:47]
	v_add_f32_e32 v88, v94, v109
	v_add_f32_e32 v88, v95, v88
	v_add_f32_e32 v88, v48, v88
	v_add_f32_e32 v109, v49, v88
	v_cvt_pk_bf16_f32 v140, v92, v93
	v_cvt_pk_bf16_f32 v141, v94, v95
	ds_read_b64_tr_b16 v[88:89], v189 offset:43008
	ds_read_b64_tr_b16 v[90:91], v189 offset:43520
	v_add_f32_e32 v92, v50, v109
	v_add_f32_e32 v92, v51, v92
	v_add_f32_e32 v92, v52, v92
	v_add_f32_e32 v92, v53, v92
	v_cvt_pk_bf16_f32 v134, v48, v49
	v_cvt_pk_bf16_f32 v135, v50, v51
	s_waitcnt lgkmcnt(13)
	v_mfma_f32_32x32x16_bf16 v[64:79], v[166:169], v[150:153], v[64:79]
	ds_read_b64_tr_b16 v[48:49], v189 offset:47104
	ds_read_b64_tr_b16 v[50:51], v189 offset:47616
	s_waitcnt lgkmcnt(14)
	v_mfma_f32_32x32x16_bf16 v[32:47], v[170:173], v[150:153], v[32:47]
	v_add_f32_e32 v92, v54, v92
	v_add_f32_e32 v92, v55, v92
	v_add_f32_e32 v92, v56, v92
	v_add_f32_e32 v109, v57, v92
	v_cvt_pk_bf16_f32 v136, v52, v53
	v_cvt_pk_bf16_f32 v137, v54, v55
	ds_read_b64_tr_b16 v[92:93], v189 offset:44032
	ds_read_b64_tr_b16 v[94:95], v189 offset:44544
	v_add_f32_e32 v52, v58, v109
	v_add_f32_e32 v52, v59, v52
	v_add_f32_e32 v52, v60, v52
	v_add_f32_e32 v109, v61, v52
	v_cvt_pk_bf16_f32 v130, v56, v57
	v_cvt_pk_bf16_f32 v131, v58, v59
	s_waitcnt lgkmcnt(14)
	v_mfma_f32_32x32x16_bf16 v[64:79], v[118:121], v[146:149], v[64:79]
	ds_read_b64_tr_b16 v[52:53], v189 offset:48128
	ds_read_b64_tr_b16 v[54:55], v189 offset:48640
	v_mfma_f32_32x32x16_bf16 v[32:47], v[104:107], v[146:149], v[32:47]
	v_add_f32_e32 v56, v62, v109
	v_add_f32_e32 v56, v63, v56
	v_add_f32_e32 v56, 0, v56
	v_cvt_pk_bf16_f32 v132, v60, v61
	v_cvt_pk_bf16_f32 v133, v62, v63
	s_nop 3
	v_exp_f32_e32 v64, v64
	v_exp_f32_e32 v65, v65
	v_exp_f32_e32 v66, v66
	v_exp_f32_e32 v67, v67
	s_nop 0
	v_exp_f32_e32 v68, v68
	v_exp_f32_e32 v69, v69
	v_exp_f32_e32 v70, v70
	v_exp_f32_e32 v71, v71
	s_nop 0
	v_exp_f32_e32 v72, v72
	v_exp_f32_e32 v73, v73
	v_exp_f32_e32 v74, v74
	v_exp_f32_e32 v75, v75
	s_nop 0
	v_exp_f32_e32 v76, v76
	v_exp_f32_e32 v77, v77
	v_exp_f32_e32 v78, v78
	v_exp_f32_e32 v79, v79
	v_exp_f32_e32 v32, v32
	v_exp_f32_e32 v33, v33
	v_exp_f32_e32 v34, v34
	v_exp_f32_e32 v35, v35
	s_nop 0
	v_exp_f32_e32 v36, v36
	v_exp_f32_e32 v37, v37
	v_exp_f32_e32 v38, v38
	v_exp_f32_e32 v39, v39
	s_nop 0
	v_exp_f32_e32 v40, v40
	v_exp_f32_e32 v41, v41
	v_exp_f32_e32 v42, v42
	v_exp_f32_e32 v43, v43
	s_nop 0
	v_exp_f32_e32 v44, v44
	v_exp_f32_e32 v45, v45
	v_exp_f32_e32 v46, v46
	v_exp_f32_e32 v47, v47
	s_waitcnt lgkmcnt(14)
; #define SBAR() __builtin_amdgcn_sched_barrier(0)
;   #define RESC() do { if constexpr (!NOMAX) if (resc) { asm volatile("s_waitcnt lgkmcnt(0)" ::: "memory"); \
;       _Pragma("unroll") for (int d_ = 0; d_ < 2 * DV2; ++d_) _Pragma("unroll") for (int r = 0; r < 16; ++r) o[d_][r] *= wsf[crow(r, hi)]; } } while (0)
;   #define PKW(P, B) cvtpk_s(P[B], P[B + 1])
;     ...
;   STEP(pB0, pB1, pA0, pA1, NT - 1, false, false, false); RESC();
;   { float sacc = pB0[0] + pB0[1]; _Pragma("unroll") for (int r = 2; r < 16; ++r) sacc += pB0[r]; _Pragma("unroll") for (int r = 0; r < 16; ++r) sacc += pB1[r]; l_reg += sacc;
;     pw0 = (u32x4){PKW(pB0, 0), PKW(pB0, 2), PKW(pB0, 4), PKW(pB0, 6)}; pw1 = (u32x4){PKW(pB0, 8), PKW(pB0, 10), PKW(pB0, 12), PKW(pB0, 14)}; pw2 = (u32x4){PKW(pB1, 0), PKW(pB1, 2), PKW(pB1, 4), PKW(pB1, 6)}; pw3 = (u32x4){PKW(pB1, 8), PKW(pB1, 10), PKW(pB1, 12), PKW(pB1, 14)};
;     SBAR(); pv(o, vb0 + DV2 * sl_cur, PAF(0), PAF(1), PAF(2), PAF(3)); if constexpr (DV2 == 2) pv(o + 2, vb0 + DV2 * sl_cur + 8192, PAF(0), PAF(1), PAF(2), PAF(3)); }
;     ...
;   { auto rr = __builtin_amdgcn_permlane32_swap(__float_as_uint(l_reg), __float_as_uint(l_reg), false, false); l_reg = __uint_as_float(rr[0]) + __uint_as_float(rr[1]); }
;   int lane_e; asm volatile("v_mbcnt_lo_u32_b32 %0, -1, 0\n\tv_mbcnt_hi_u32_b32 %0, -1, %0" : "=v"(lane_e));
;   const int r32e = lane_e & 31, hie = lane_e >> 5;
;   if (hie == 0) wsf[32 + r32e] = l_reg; asm volatile("s_waitcnt lgkmcnt(0)" ::: "memory");
	v_mfma_f32_32x32x16_bf16 v[0:15], v[142:145], v[96:99], v[0:15]
	v_add_f32_e32 v57, v64, v65
	v_add_f32_e32 v57, v66, v57
	v_add_f32_e32 v57, v67, v57
	v_add_f32_e32 v57, v68, v57
	v_add_f32_e32 v57, v69, v57
	v_add_f32_e32 v57, v70, v57
	v_add_f32_e32 v57, v71, v57
	s_waitcnt lgkmcnt(12)
	v_mfma_f32_32x32x16_bf16 v[16:31], v[142:145], v[80:83], v[16:31]
	v_add_f32_e32 v57, v72, v57
	v_add_f32_e32 v57, v73, v57
	v_add_f32_e32 v57, v74, v57
	v_add_f32_e32 v57, v75, v57
	v_add_f32_e32 v57, v76, v57
	v_add_f32_e32 v57, v77, v57
	v_add_f32_e32 v57, v78, v57
	s_waitcnt lgkmcnt(10)
	v_mfma_f32_32x32x16_bf16 v[0:15], v[138:141], v[100:103], v[0:15]
	v_add_f32_e32 v57, v79, v57
	v_add_f32_e32 v57, v32, v57
	v_add_f32_e32 v57, v33, v57
	v_add_f32_e32 v57, v34, v57
	v_add_f32_e32 v57, v35, v57
	v_add_f32_e32 v57, v36, v57
	v_add_f32_e32 v57, v37, v57
	s_waitcnt lgkmcnt(8)
	v_mfma_f32_32x32x16_bf16 v[16:31], v[138:141], v[84:87], v[16:31]
	v_add_f32_e32 v57, v38, v57
	v_add_f32_e32 v57, v39, v57
	v_add_f32_e32 v57, v40, v57
	v_add_f32_e32 v57, v41, v57
	v_add_f32_e32 v57, v42, v57
	v_add_f32_e32 v57, v43, v57
	v_add_f32_e32 v57, v44, v57
	s_waitcnt lgkmcnt(6)
	v_mfma_f32_32x32x16_bf16 v[0:15], v[134:137], v[88:91], v[0:15]
	v_add_f32_e32 v57, v45, v57
	v_add_f32_e32 v57, v46, v57
	v_add_f32_e32 v57, v47, v57
	v_add_f32_e32 v56, v108, v56
	v_add_f32_e32 v56, v56, v57
	v_cvt_pk_bf16_f32 v32, v32, v33
	v_cvt_pk_bf16_f32 v33, v34, v35
	s_waitcnt lgkmcnt(4)
	v_mfma_f32_32x32x16_bf16 v[16:31], v[134:137], v[48:51], v[16:31]
	v_cvt_pk_bf16_f32 v58, v64, v65
	v_cvt_pk_bf16_f32 v59, v66, v67
	v_cvt_pk_bf16_f32 v60, v68, v69
	v_cvt_pk_bf16_f32 v61, v70, v71
	v_cvt_pk_bf16_f32 v62, v72, v73
	v_cvt_pk_bf16_f32 v63, v74, v75
	v_cvt_pk_bf16_f32 v64, v76, v77
	s_waitcnt lgkmcnt(2)
	v_mfma_f32_32x32x16_bf16 v[0:15], v[130:133], v[92:95], v[0:15]
	v_cvt_pk_bf16_f32 v65, v78, v79
	v_cvt_pk_bf16_f32 v34, v36, v37
	v_cvt_pk_bf16_f32 v35, v38, v39
	v_cvt_pk_bf16_f32 v36, v40, v41
	v_cvt_pk_bf16_f32 v37, v42, v43
	v_cvt_pk_bf16_f32 v38, v44, v45
	v_cvt_pk_bf16_f32 v39, v46, v47
	s_waitcnt lgkmcnt(0)
	v_mfma_f32_32x32x16_bf16 v[16:31], v[130:133], v[52:55], v[16:31]
	ds_read_b64_tr_b16 v[40:41],v188 offset:0
	ds_read_b64_tr_b16 v[42:43],v188 offset:512
	ds_read_b64_tr_b16 v[44:45],v188 offset:1024
	ds_read_b64_tr_b16 v[46:47],v188 offset:1536
	ds_read_b64_tr_b16 v[48:49],v188 offset:2048
	ds_read_b64_tr_b16 v[50:51],v188 offset:2560
	ds_read_b64_tr_b16 v[52:53],v188 offset:3072
	ds_read_b64_tr_b16 v[54:55],v188 offset:3584
	s_waitcnt lgkmcnt(0)
	s_nop 0
	v_mfma_f32_32x32x16_bf16 v[0:15], v[58:61], v[40:43], v[0:15]
	ds_read_b64_tr_b16 v[40:41],v188 offset:4096
	ds_read_b64_tr_b16 v[42:43],v188 offset:4608
	v_mfma_f32_32x32x16_bf16 v[0:15], v[62:65], v[44:47], v[0:15]
	ds_read_b64_tr_b16 v[44:45],v188 offset:5120
	ds_read_b64_tr_b16 v[46:47],v188 offset:5632
	v_mfma_f32_32x32x16_bf16 v[0:15], v[32:35], v[48:51], v[0:15]
	ds_read_b64_tr_b16 v[48:49],v188 offset:6144
	ds_read_b64_tr_b16 v[50:51],v188 offset:6656
	v_mfma_f32_32x32x16_bf16 v[0:15], v[36:39], v[52:55], v[0:15]
	ds_read_b64_tr_b16 v[52:53],v188 offset:7168
	ds_read_b64_tr_b16 v[54:55],v188 offset:7680
	s_waitcnt lgkmcnt(0)
	v_mfma_f32_32x32x16_bf16 v[16:31], v[58:61], v[40:43], v[16:31]
	v_mfma_f32_32x32x16_bf16 v[16:31], v[62:65], v[44:47], v[16:31]
	v_mfma_f32_32x32x16_bf16 v[16:31], v[32:35], v[48:51], v[16:31]
	v_mov_b32_e32 v33, v56
	s_nop 1
	v_permlane32_swap_b32_e32 v56, v33
	v_mbcnt_lo_u32_b32 v32, -1, 0
	v_mbcnt_hi_u32_b32 v32, -1, v32
	s_nop 0
	v_cmp_gt_u32_e32 vcc, 32, v32
	v_mfma_f32_32x32x16_bf16 v[16:31], v[36:39], v[52:55], v[16:31]
	s_and_saveexec_b64 s[8:9], vcc
	s_cbranch_execz .LBB0_968
	v_add_f32_e32 v33, v56, v33
	v_lshl_add_u32 v34, v32, 2, s16
	ds_write_b32 v34, v33 offset:49280
	s_branch .LBB0_968
